# differential attention: the 4 K fragment LDS reads of a sub-tile issued together (3 bodies), QK MFMAs wait with counted lgkmcnt (on v99)
# speedup vs baseline: 1.0077x; 1.0000x over previous
.LBB0_311:
	ds_read_b128 v[6:9], v4 offset:12288
	ds_read_b128 v[10:13], v5 offset:12288
	ds_read_b128 v[132:135], v2 offset:12288
	ds_read_b128 v[136:139], v3 offset:12288
	s_add_i32 s8, s58, 0x7f
	s_cmp_gt_i32 s8, s54
	s_mov_b64 s[8:9], -1
	s_waitcnt lgkmcnt(3)
	v_mfma_f32_32x32x16_bf16 v[96:111], v[6:9], v[116:119], 0
	s_waitcnt lgkmcnt(2)
	v_mfma_f32_32x32x16_bf16 v[96:111], v[10:13], v[120:123], v[96:111]
	s_waitcnt lgkmcnt(1)
	v_mfma_f32_32x32x16_bf16 v[96:111], v[132:135], v[124:127], v[96:111]
	s_waitcnt lgkmcnt(0)
	v_mfma_f32_32x32x16_bf16 v[96:111], v[136:139], v[128:131], v[96:111]
	s_cbranch_scc1 .LBB0_313
	s_nop 10
	v_fmamk_f32 v80, v96, 0x3e38aa3b, v216
	v_fma_f32 v81, v97, s30, -v214
	v_fmamk_f32 v82, v98, 0x3e38aa3b, v217
	v_max3_f32 v7, v80, s52, v81
	v_fmamk_f32 v83, v99, 0x3e38aa3b, v218
	v_add_u32_e32 v6, s58, v188
	v_fmamk_f32 v84, v100, 0x3e38aa3b, v219
	v_max3_f32 v7, v7, v82, v83
	v_fmamk_f32 v85, v101, 0x3e38aa3b, v220
	v_add_u32_e32 v6, 0x60, v6
	v_fmamk_f32 v86, v102, 0x3e38aa3b, v221
	v_max3_f32 v7, v7, v84, v85
	v_fmamk_f32 v87, v103, 0x3e38aa3b, v222
	v_cvt_f32_i32_e32 v6, v6
	v_fmamk_f32 v88, v104, 0x3e38aa3b, v223
	v_max3_f32 v7, v7, v86, v87
	v_fmamk_f32 v89, v105, 0x3e38aa3b, v224
	v_fmamk_f32 v90, v106, 0x3e38aa3b, v225
	v_max3_f32 v7, v7, v88, v89
	v_fmamk_f32 v91, v107, 0x3e38aa3b, v226
	v_fmamk_f32 v92, v108, 0x3e38aa3b, v227
	v_max3_f32 v7, v7, v90, v91
	v_fmamk_f32 v93, v109, 0x3e38aa3b, v228
	v_fmamk_f32 v94, v110, 0x3e38aa3b, v229
	v_max3_f32 v7, v7, v92, v93
	v_fmamk_f32 v95, v111, 0x3e38aa3b, v230
	v_mul_f32_e64 v6, -v214, v6
	v_max3_f32 v7, v7, v94, v95
	s_mov_b64 s[8:9], 0

.LBB0_334:
	ds_read_b128 v[6:9], v4 offset:8192
	ds_read_b128 v[10:13], v5 offset:8192
	ds_read_b128 v[132:135], v2 offset:8192
	ds_read_b128 v[136:139], v3 offset:8192
	s_add_i32 s8, s58, 0x5f
	s_cmp_gt_i32 s8, s54
	s_mov_b64 s[8:9], -1
	s_waitcnt lgkmcnt(3)
	v_mfma_f32_32x32x16_bf16 v[96:111], v[6:9], v[116:119], 0
	s_waitcnt lgkmcnt(2)
	v_mfma_f32_32x32x16_bf16 v[96:111], v[10:13], v[120:123], v[96:111]
	s_waitcnt lgkmcnt(1)
	v_mfma_f32_32x32x16_bf16 v[96:111], v[132:135], v[124:127], v[96:111]
	s_waitcnt lgkmcnt(0)
	v_mfma_f32_32x32x16_bf16 v[96:111], v[136:139], v[128:131], v[96:111]
	s_cbranch_scc1 .LBB0_336
	s_nop 10
	v_fmamk_f32 v80, v96, 0x3e38aa3b, v216
	v_fma_f32 v81, v97, s30, -v214
	v_fmamk_f32 v82, v98, 0x3e38aa3b, v217
	v_max3_f32 v7, v80, s52, v81
	v_fmamk_f32 v83, v99, 0x3e38aa3b, v218
	v_fmamk_f32 v84, v100, 0x3e38aa3b, v219
	v_max3_f32 v7, v7, v82, v83
	v_fmamk_f32 v85, v101, 0x3e38aa3b, v220
	v_add3_u32 v6, v188, s58, 64
	v_fmamk_f32 v86, v102, 0x3e38aa3b, v221
	v_max3_f32 v7, v7, v84, v85
	v_fmamk_f32 v87, v103, 0x3e38aa3b, v222
	v_cvt_f32_i32_e32 v6, v6
	v_fmamk_f32 v88, v104, 0x3e38aa3b, v223
	v_max3_f32 v7, v7, v86, v87
	v_fmamk_f32 v89, v105, 0x3e38aa3b, v224
	v_fmamk_f32 v90, v106, 0x3e38aa3b, v225
	v_max3_f32 v7, v7, v88, v89
	v_fmamk_f32 v91, v107, 0x3e38aa3b, v226
	v_fmamk_f32 v92, v108, 0x3e38aa3b, v227
	v_max3_f32 v7, v7, v90, v91
	v_fmamk_f32 v93, v109, 0x3e38aa3b, v228
	v_fmamk_f32 v94, v110, 0x3e38aa3b, v229
	v_max3_f32 v7, v7, v92, v93
	v_fmamk_f32 v95, v111, 0x3e38aa3b, v230
	v_mul_f32_e64 v6, -v214, v6
	v_max3_f32 v7, v7, v94, v95
	s_mov_b64 s[8:9], 0

.LBB0_357:
	ds_read_b128 v[6:9], v4 offset:4096
	ds_read_b128 v[10:13], v5 offset:4096
	ds_read_b128 v[132:135], v2 offset:4096
	ds_read_b128 v[136:139], v3 offset:4096
	s_add_i32 s8, s58, 63
	s_cmp_gt_i32 s8, s54
	s_mov_b64 s[8:9], -1
	s_waitcnt lgkmcnt(3)
	v_mfma_f32_32x32x16_bf16 v[96:111], v[6:9], v[116:119], 0
	s_waitcnt lgkmcnt(2)
	v_mfma_f32_32x32x16_bf16 v[96:111], v[10:13], v[120:123], v[96:111]
	s_waitcnt lgkmcnt(1)
	v_mfma_f32_32x32x16_bf16 v[96:111], v[132:135], v[124:127], v[96:111]
	s_waitcnt lgkmcnt(0)
	v_mfma_f32_32x32x16_bf16 v[96:111], v[136:139], v[128:131], v[96:111]
	s_cbranch_scc1 .LBB0_359
	s_nop 10
	v_fmamk_f32 v80, v96, 0x3e38aa3b, v216
	v_fma_f32 v81, v97, s30, -v214
	v_fmamk_f32 v82, v98, 0x3e38aa3b, v217
	v_max3_f32 v7, v80, s52, v81
	v_fmamk_f32 v83, v99, 0x3e38aa3b, v218
	v_fmamk_f32 v84, v100, 0x3e38aa3b, v219
	v_max3_f32 v7, v7, v82, v83
	v_fmamk_f32 v85, v101, 0x3e38aa3b, v220
	v_add3_u32 v6, v188, s58, 32
	v_fmamk_f32 v86, v102, 0x3e38aa3b, v221
	v_max3_f32 v7, v7, v84, v85
	v_fmamk_f32 v87, v103, 0x3e38aa3b, v222
	v_cvt_f32_i32_e32 v6, v6
	v_fmamk_f32 v88, v104, 0x3e38aa3b, v223
	v_max3_f32 v7, v7, v86, v87
	v_fmamk_f32 v89, v105, 0x3e38aa3b, v224
	v_fmamk_f32 v90, v106, 0x3e38aa3b, v225
	v_max3_f32 v7, v7, v88, v89
	v_fmamk_f32 v91, v107, 0x3e38aa3b, v226
	v_fmamk_f32 v92, v108, 0x3e38aa3b, v227
	v_max3_f32 v7, v7, v90, v91
	v_fmamk_f32 v93, v109, 0x3e38aa3b, v228
	v_fmamk_f32 v94, v110, 0x3e38aa3b, v229
	v_max3_f32 v7, v7, v92, v93
	v_fmamk_f32 v95, v111, 0x3e38aa3b, v230
	v_mul_f32_e64 v6, -v214, v6
	v_max3_f32 v7, v7, v94, v95
	s_mov_b64 s[8:9], 0
